# merged-branch GEMM: gate mid-hook and final epilogue rewritten with 3-5 deep pipelined gate loads (counted vmcnt) using phase-free VGPRs
# speedup vs baseline: 1.0688x; 1.0086x over previous
; __device__ __forceinline__ int otid() { int t = (int)threadIdx.x; asm volatile("" : "+v"(t)); return t; }
;     __device__ __forceinline__ void mid(f32x4 (&acc)[2][2][4][2], const Unit& u, int wr, int wc) const {
;         const int ln_ = otid() & 63, fr = ln_ & 15, fq = ln_ >> 4;
;         const size_t rowb = (size_t)u.pm * BM + wr * 64 + fr; const int col0 = u.pn * BM + wc * 32 + 8 * fq;
; #pragma unroll
;         for (int ai = 0; ai < 2; ++ai)
; #pragma unroll
;             for (int m = 0; m < 4; ++m) { const bf16_t* sp = SIG + (rowb + ai * HALF + m * 16) * 2048 + col0;
; #pragma unroll
;                 for (int bj = 0; bj < 2; ++bj) { const u32x4 sa = *(const u32x4*)(sp + bj * HALF), sb = *(const u32x4*)(sp + 1024 + bj * HALF);
;                     f32x4& v0 = acc[ai][bj][m][0]; f32x4& v1 = acc[ai][bj][m][1];
;                     v0[0] *= bf_lo(sa.x) * __builtin_amdgcn_rcpf(1e-30f + bf_lo(sb.x)); v0[1] *= bf_hi(sa.x) * __builtin_amdgcn_rcpf(1e-30f + bf_hi(sb.x));
;                     v0[2] *= bf_lo(sa.y) * __builtin_amdgcn_rcpf(1e-30f + bf_lo(sb.y)); v0[3] *= bf_hi(sa.y) * __builtin_amdgcn_rcpf(1e-30f + bf_hi(sb.y));
;                     v1[0] *= bf_lo(sa.z) * __builtin_amdgcn_rcpf(1e-30f + bf_lo(sb.z)); v1[1] *= bf_hi(sa.z) * __builtin_amdgcn_rcpf(1e-30f + bf_hi(sb.z));
;                     v1[2] *= bf_lo(sa.w) * __builtin_amdgcn_rcpf(1e-30f + bf_lo(sb.w)); v1[3] *= bf_hi(sa.w) * __builtin_amdgcn_rcpf(1e-30f + bf_hi(sb.w)); }
;                 asm volatile("" ::: "memory"); }
.LBB0_213:
	s_cmpk_lg_i32 s6, 0x400
	s_cbranch_scc1 .LBB0_212
	v_mov_b32_e32 v131, v221
	v_mov_b32_e32 v133, s60
	v_lshrrev_b32_e32 v130, 1, v131
	v_and_or_b32 v132, v131, 15, s56
	v_and_or_b32 v130, v130, 24, s65
	v_lshlrev_b64 v[132:133], 12, v[132:133]
	v_ashrrev_i32_e32 v131, 31, v130
	v_lshl_add_u64 v[132:133], s[2:3], 0, v[132:133]
	v_lshl_add_u64 v[134:135], v[130:131], 1, v[132:133]
	global_load_dwordx4 v[130:133], v[134:135], off
	global_load_dwordx4 v[154:157], v[134:135], off offset:2048
	global_load_dwordx4 v[234:237], v[134:135], off offset:256
	global_load_dwordx4 v[242:245], v[134:135], off offset:2304
	v_add_co_u32_e32 v134, vcc, 0x10000, v134
	s_nop 1
	v_addc_co_u32_e32 v135, vcc, 0, v135, vcc
	global_load_dwordx4 v[238:241], v[134:135], off
	global_load_dwordx4 v[246:249], v[134:135], off offset:2048
	s_waitcnt vmcnt(4)
	v_lshlrev_b32_e32 v158, 16, v130
	v_and_b32_e32 v159, 0xffff0000, v130
	v_lshlrev_b32_e32 v136, 16, v154
	v_and_b32_e32 v137, 0xffff0000, v154
	v_lshlrev_b32_e32 v250, 16, v131
	v_and_b32_e32 v251, 0xffff0000, v131
	v_lshlrev_b32_e32 v252, 16, v155
	v_and_b32_e32 v253, 0xffff0000, v155
	v_add_f32_e32 v136, 0xda24260, v136
	v_add_f32_e32 v137, 0xda24260, v137
	v_add_f32_e32 v252, 0xda24260, v252
	v_add_f32_e32 v253, 0xda24260, v253
	v_rcp_f32_e32 v136, v136
	v_rcp_f32_e32 v137, v137
	v_rcp_f32_e32 v252, v252
	v_rcp_f32_e32 v253, v253
	v_pk_mul_f32 v[136:137], v[136:137], v[158:159]
	v_pk_mul_f32 v[252:253], v[252:253], v[250:251]
	v_pk_mul_f32 v[126:127], v[126:127], v[136:137]
	v_pk_mul_f32 v[128:129], v[128:129], v[252:253]
	v_lshlrev_b32_e32 v158, 16, v132
	v_and_b32_e32 v159, 0xffff0000, v132
	v_lshlrev_b32_e32 v136, 16, v156
	v_and_b32_e32 v137, 0xffff0000, v156
	v_lshlrev_b32_e32 v250, 16, v133
	v_and_b32_e32 v251, 0xffff0000, v133
	v_lshlrev_b32_e32 v252, 16, v157
	v_and_b32_e32 v253, 0xffff0000, v157
	v_add_f32_e32 v136, 0xda24260, v136
	v_add_f32_e32 v137, 0xda24260, v137
	v_add_f32_e32 v252, 0xda24260, v252
	v_add_f32_e32 v253, 0xda24260, v253
	v_rcp_f32_e32 v136, v136
	v_rcp_f32_e32 v137, v137
	v_rcp_f32_e32 v252, v252
	v_rcp_f32_e32 v253, v253
	v_pk_mul_f32 v[136:137], v[136:137], v[158:159]
	v_pk_mul_f32 v[252:253], v[252:253], v[250:251]
	v_pk_mul_f32 v[122:123], v[122:123], v[136:137]
	v_pk_mul_f32 v[124:125], v[124:125], v[252:253]
	global_load_dwordx4 v[130:133], v[134:135], off offset:256
	global_load_dwordx4 v[154:157], v[134:135], off offset:2304
	s_waitcnt vmcnt(4)
	v_lshlrev_b32_e32 v158, 16, v234
	v_and_b32_e32 v159, 0xffff0000, v234
	v_lshlrev_b32_e32 v136, 16, v242
	v_and_b32_e32 v137, 0xffff0000, v242
	v_lshlrev_b32_e32 v250, 16, v235
	v_and_b32_e32 v251, 0xffff0000, v235
	v_lshlrev_b32_e32 v252, 16, v243
	v_and_b32_e32 v253, 0xffff0000, v243
	v_add_f32_e32 v136, 0xda24260, v136
	v_add_f32_e32 v137, 0xda24260, v137
	v_add_f32_e32 v252, 0xda24260, v252
	v_add_f32_e32 v253, 0xda24260, v253
	v_rcp_f32_e32 v136, v136
	v_rcp_f32_e32 v137, v137
	v_rcp_f32_e32 v252, v252
	v_rcp_f32_e32 v253, v253
	v_pk_mul_f32 v[136:137], v[136:137], v[158:159]
	v_pk_mul_f32 v[252:253], v[252:253], v[250:251]
	v_pk_mul_f32 v[118:119], v[118:119], v[136:137]
	v_pk_mul_f32 v[120:121], v[120:121], v[252:253]
	v_lshlrev_b32_e32 v158, 16, v236
	v_and_b32_e32 v159, 0xffff0000, v236
	v_lshlrev_b32_e32 v136, 16, v244
	v_and_b32_e32 v137, 0xffff0000, v244
	v_lshlrev_b32_e32 v250, 16, v237
	v_and_b32_e32 v251, 0xffff0000, v237
	v_lshlrev_b32_e32 v252, 16, v245
	v_and_b32_e32 v253, 0xffff0000, v245
	v_add_f32_e32 v136, 0xda24260, v136
	v_add_f32_e32 v137, 0xda24260, v137
	v_add_f32_e32 v252, 0xda24260, v252
	v_add_f32_e32 v253, 0xda24260, v253
	v_rcp_f32_e32 v136, v136
	v_rcp_f32_e32 v137, v137
	v_rcp_f32_e32 v252, v252
	v_rcp_f32_e32 v253, v253
	v_pk_mul_f32 v[136:137], v[136:137], v[158:159]
	v_pk_mul_f32 v[252:253], v[252:253], v[250:251]
	v_pk_mul_f32 v[114:115], v[114:115], v[136:137]
	v_pk_mul_f32 v[116:117], v[116:117], v[252:253]
	v_add_co_u32_e32 v134, vcc, 0x10000, v134
	s_nop 1
	v_addc_co_u32_e32 v135, vcc, 0, v135, vcc
	global_load_dwordx4 v[234:237], v[134:135], off
	global_load_dwordx4 v[242:245], v[134:135], off offset:2048
	s_waitcnt vmcnt(4)
	v_lshlrev_b32_e32 v158, 16, v238
	v_and_b32_e32 v159, 0xffff0000, v238
	v_lshlrev_b32_e32 v136, 16, v246
	v_and_b32_e32 v137, 0xffff0000, v246
	v_lshlrev_b32_e32 v250, 16, v239
	v_and_b32_e32 v251, 0xffff0000, v239
	v_lshlrev_b32_e32 v252, 16, v247
	v_and_b32_e32 v253, 0xffff0000, v247
	v_add_f32_e32 v136, 0xda24260, v136
	v_add_f32_e32 v137, 0xda24260, v137
	v_add_f32_e32 v252, 0xda24260, v252
	v_add_f32_e32 v253, 0xda24260, v253
	v_rcp_f32_e32 v136, v136
	v_rcp_f32_e32 v137, v137
	v_rcp_f32_e32 v252, v252
	v_rcp_f32_e32 v253, v253
	v_pk_mul_f32 v[136:137], v[136:137], v[158:159]
	v_pk_mul_f32 v[252:253], v[252:253], v[250:251]
	v_pk_mul_f32 v[110:111], v[110:111], v[136:137]
	v_pk_mul_f32 v[112:113], v[112:113], v[252:253]
	v_lshlrev_b32_e32 v158, 16, v240
	v_and_b32_e32 v159, 0xffff0000, v240
	v_lshlrev_b32_e32 v136, 16, v248
	v_and_b32_e32 v137, 0xffff0000, v248
	v_lshlrev_b32_e32 v250, 16, v241
	v_and_b32_e32 v251, 0xffff0000, v241
	v_lshlrev_b32_e32 v252, 16, v249
	v_and_b32_e32 v253, 0xffff0000, v249
	v_add_f32_e32 v136, 0xda24260, v136
	v_add_f32_e32 v137, 0xda24260, v137
	v_add_f32_e32 v252, 0xda24260, v252
	v_add_f32_e32 v253, 0xda24260, v253
	v_rcp_f32_e32 v136, v136
	v_rcp_f32_e32 v137, v137
	v_rcp_f32_e32 v252, v252
	v_rcp_f32_e32 v253, v253
	v_pk_mul_f32 v[136:137], v[136:137], v[158:159]
	v_pk_mul_f32 v[252:253], v[252:253], v[250:251]
	v_pk_mul_f32 v[106:107], v[106:107], v[136:137]
	v_pk_mul_f32 v[108:109], v[108:109], v[252:253]
	global_load_dwordx4 v[238:241], v[134:135], off offset:256
	global_load_dwordx4 v[246:249], v[134:135], off offset:2304
	s_waitcnt vmcnt(4)
; __device__ __forceinline__ int otid() { int t = (int)threadIdx.x; asm volatile("" : "+v"(t)); return t; }
;     __device__ __forceinline__ void mid(f32x4 (&acc)[2][2][4][2], const Unit& u, int wr, int wc) const {
;         const int ln_ = otid() & 63, fr = ln_ & 15, fq = ln_ >> 4;
;         const size_t rowb = (size_t)u.pm * BM + wr * 64 + fr; const int col0 = u.pn * BM + wc * 32 + 8 * fq;
; #pragma unroll
;         for (int ai = 0; ai < 2; ++ai)
; #pragma unroll
;             for (int m = 0; m < 4; ++m) { const bf16_t* sp = SIG + (rowb + ai * HALF + m * 16) * 2048 + col0;
; #pragma unroll
;                 for (int bj = 0; bj < 2; ++bj) { const u32x4 sa = *(const u32x4*)(sp + bj * HALF), sb = *(const u32x4*)(sp + 1024 + bj * HALF);
;                     f32x4& v0 = acc[ai][bj][m][0]; f32x4& v1 = acc[ai][bj][m][1];
;                     v0[0] *= bf_lo(sa.x) * __builtin_amdgcn_rcpf(1e-30f + bf_lo(sb.x)); v0[1] *= bf_hi(sa.x) * __builtin_amdgcn_rcpf(1e-30f + bf_hi(sb.x));
;                     v0[2] *= bf_lo(sa.y) * __builtin_amdgcn_rcpf(1e-30f + bf_lo(sb.y)); v0[3] *= bf_hi(sa.y) * __builtin_amdgcn_rcpf(1e-30f + bf_hi(sb.y));
;                     v1[0] *= bf_lo(sa.z) * __builtin_amdgcn_rcpf(1e-30f + bf_lo(sb.z)); v1[1] *= bf_hi(sa.z) * __builtin_amdgcn_rcpf(1e-30f + bf_hi(sb.z));
;                     v1[2] *= bf_lo(sa.w) * __builtin_amdgcn_rcpf(1e-30f + bf_lo(sb.w)); v1[3] *= bf_hi(sa.w) * __builtin_amdgcn_rcpf(1e-30f + bf_hi(sb.w)); }
;                 asm volatile("" ::: "memory"); }
	v_lshlrev_b32_e32 v158, 16, v130
	v_and_b32_e32 v159, 0xffff0000, v130
	v_lshlrev_b32_e32 v136, 16, v154
	v_and_b32_e32 v137, 0xffff0000, v154
	v_lshlrev_b32_e32 v250, 16, v131
	v_and_b32_e32 v251, 0xffff0000, v131
	v_lshlrev_b32_e32 v252, 16, v155
	v_and_b32_e32 v253, 0xffff0000, v155
	v_add_f32_e32 v136, 0xda24260, v136
	v_add_f32_e32 v137, 0xda24260, v137
	v_add_f32_e32 v252, 0xda24260, v252
	v_add_f32_e32 v253, 0xda24260, v253
	v_rcp_f32_e32 v136, v136
	v_rcp_f32_e32 v137, v137
	v_rcp_f32_e32 v252, v252
	v_rcp_f32_e32 v253, v253
	v_pk_mul_f32 v[136:137], v[136:137], v[158:159]
	v_pk_mul_f32 v[252:253], v[252:253], v[250:251]
	v_pk_mul_f32 v[102:103], v[102:103], v[136:137]
	v_pk_mul_f32 v[104:105], v[104:105], v[252:253]
	v_lshlrev_b32_e32 v158, 16, v132
	v_and_b32_e32 v159, 0xffff0000, v132
	v_lshlrev_b32_e32 v136, 16, v156
	v_and_b32_e32 v137, 0xffff0000, v156
	v_lshlrev_b32_e32 v250, 16, v133
	v_and_b32_e32 v251, 0xffff0000, v133
	v_lshlrev_b32_e32 v252, 16, v157
	v_and_b32_e32 v253, 0xffff0000, v157
	v_add_f32_e32 v136, 0xda24260, v136
	v_add_f32_e32 v137, 0xda24260, v137
	v_add_f32_e32 v252, 0xda24260, v252
	v_add_f32_e32 v253, 0xda24260, v253
	v_rcp_f32_e32 v136, v136
	v_rcp_f32_e32 v137, v137
	v_rcp_f32_e32 v252, v252
	v_rcp_f32_e32 v253, v253
	v_pk_mul_f32 v[136:137], v[136:137], v[158:159]
	v_pk_mul_f32 v[252:253], v[252:253], v[250:251]
	v_pk_mul_f32 v[98:99], v[98:99], v[136:137]
	v_pk_mul_f32 v[100:101], v[100:101], v[252:253]
	v_add_co_u32_e32 v134, vcc, 0x10000, v134
	s_nop 1
	v_addc_co_u32_e32 v135, vcc, 0, v135, vcc
	global_load_dwordx4 v[130:133], v[134:135], off
	global_load_dwordx4 v[154:157], v[134:135], off offset:2048
	s_waitcnt vmcnt(4)
	v_lshlrev_b32_e32 v158, 16, v234
	v_and_b32_e32 v159, 0xffff0000, v234
	v_lshlrev_b32_e32 v136, 16, v242
	v_and_b32_e32 v137, 0xffff0000, v242
	v_lshlrev_b32_e32 v250, 16, v235
	v_and_b32_e32 v251, 0xffff0000, v235
	v_lshlrev_b32_e32 v252, 16, v243
	v_and_b32_e32 v253, 0xffff0000, v243
	v_add_f32_e32 v136, 0xda24260, v136
	v_add_f32_e32 v137, 0xda24260, v137
	v_add_f32_e32 v252, 0xda24260, v252
	v_add_f32_e32 v253, 0xda24260, v253
	v_rcp_f32_e32 v136, v136
	v_rcp_f32_e32 v137, v137
	v_rcp_f32_e32 v252, v252
	v_rcp_f32_e32 v253, v253
	v_pk_mul_f32 v[136:137], v[136:137], v[158:159]
	v_pk_mul_f32 v[252:253], v[252:253], v[250:251]
	v_pk_mul_f32 v[94:95], v[94:95], v[136:137]
	v_pk_mul_f32 v[96:97], v[96:97], v[252:253]
	v_lshlrev_b32_e32 v158, 16, v236
	v_and_b32_e32 v159, 0xffff0000, v236
	v_lshlrev_b32_e32 v136, 16, v244
	v_and_b32_e32 v137, 0xffff0000, v244
	v_lshlrev_b32_e32 v250, 16, v237
	v_and_b32_e32 v251, 0xffff0000, v237
	v_lshlrev_b32_e32 v252, 16, v245
	v_and_b32_e32 v253, 0xffff0000, v245
	v_add_f32_e32 v136, 0xda24260, v136
	v_add_f32_e32 v137, 0xda24260, v137
	v_add_f32_e32 v252, 0xda24260, v252
	v_add_f32_e32 v253, 0xda24260, v253
	v_rcp_f32_e32 v136, v136
	v_rcp_f32_e32 v137, v137
	v_rcp_f32_e32 v252, v252
	v_rcp_f32_e32 v253, v253
	v_pk_mul_f32 v[136:137], v[136:137], v[158:159]
	v_pk_mul_f32 v[252:253], v[252:253], v[250:251]
	v_pk_mul_f32 v[90:91], v[90:91], v[136:137]
	v_pk_mul_f32 v[92:93], v[92:93], v[252:253]
	global_load_dwordx4 v[234:237], v[134:135], off offset:256
	global_load_dwordx4 v[242:245], v[134:135], off offset:2304
	s_waitcnt vmcnt(4)
	v_lshlrev_b32_e32 v158, 16, v238
	v_and_b32_e32 v159, 0xffff0000, v238
	v_lshlrev_b32_e32 v136, 16, v246
	v_and_b32_e32 v137, 0xffff0000, v246
	v_lshlrev_b32_e32 v250, 16, v239
	v_and_b32_e32 v251, 0xffff0000, v239
	v_lshlrev_b32_e32 v252, 16, v247
	v_and_b32_e32 v253, 0xffff0000, v247
	v_add_f32_e32 v136, 0xda24260, v136
	v_add_f32_e32 v137, 0xda24260, v137
	v_add_f32_e32 v252, 0xda24260, v252
	v_add_f32_e32 v253, 0xda24260, v253
	v_rcp_f32_e32 v136, v136
	v_rcp_f32_e32 v137, v137
	v_rcp_f32_e32 v252, v252
	v_rcp_f32_e32 v253, v253
	v_pk_mul_f32 v[136:137], v[136:137], v[158:159]
	v_pk_mul_f32 v[252:253], v[252:253], v[250:251]
	v_pk_mul_f32 v[86:87], v[86:87], v[136:137]
	v_pk_mul_f32 v[88:89], v[88:89], v[252:253]
	v_lshlrev_b32_e32 v158, 16, v240
	v_and_b32_e32 v159, 0xffff0000, v240
	v_lshlrev_b32_e32 v136, 16, v248
	v_and_b32_e32 v137, 0xffff0000, v248
	v_lshlrev_b32_e32 v250, 16, v241
	v_and_b32_e32 v251, 0xffff0000, v241
	v_lshlrev_b32_e32 v252, 16, v249
	v_and_b32_e32 v253, 0xffff0000, v249
	v_add_f32_e32 v136, 0xda24260, v136
	v_add_f32_e32 v137, 0xda24260, v137
	v_add_f32_e32 v252, 0xda24260, v252
	v_add_f32_e32 v253, 0xda24260, v253
	v_rcp_f32_e32 v136, v136
	v_rcp_f32_e32 v137, v137
	v_rcp_f32_e32 v252, v252
	v_rcp_f32_e32 v253, v253
	v_pk_mul_f32 v[136:137], v[136:137], v[158:159]
	v_pk_mul_f32 v[252:253], v[252:253], v[250:251]
	v_pk_mul_f32 v[82:83], v[82:83], v[136:137]
	v_pk_mul_f32 v[84:85], v[84:85], v[252:253]
	v_add_co_u32_e32 v134, vcc, 0x50000, v134
	s_nop 1
	v_addc_co_u32_e32 v135, vcc, 0, v135, vcc
	global_load_dwordx4 v[238:241], v[134:135], off
	global_load_dwordx4 v[246:249], v[134:135], off offset:2048
	s_waitcnt vmcnt(4)
; __device__ __forceinline__ int otid() { int t = (int)threadIdx.x; asm volatile("" : "+v"(t)); return t; }
;     __device__ __forceinline__ void mid(f32x4 (&acc)[2][2][4][2], const Unit& u, int wr, int wc) const {
;         const int ln_ = otid() & 63, fr = ln_ & 15, fq = ln_ >> 4;
;         const size_t rowb = (size_t)u.pm * BM + wr * 64 + fr; const int col0 = u.pn * BM + wc * 32 + 8 * fq;
; #pragma unroll
;         for (int ai = 0; ai < 2; ++ai)
; #pragma unroll
;             for (int m = 0; m < 4; ++m) { const bf16_t* sp = SIG + (rowb + ai * HALF + m * 16) * 2048 + col0;
; #pragma unroll
;                 for (int bj = 0; bj < 2; ++bj) { const u32x4 sa = *(const u32x4*)(sp + bj * HALF), sb = *(const u32x4*)(sp + 1024 + bj * HALF);
;                     f32x4& v0 = acc[ai][bj][m][0]; f32x4& v1 = acc[ai][bj][m][1];
;                     v0[0] *= bf_lo(sa.x) * __builtin_amdgcn_rcpf(1e-30f + bf_lo(sb.x)); v0[1] *= bf_hi(sa.x) * __builtin_amdgcn_rcpf(1e-30f + bf_hi(sb.x));
;                     v0[2] *= bf_lo(sa.y) * __builtin_amdgcn_rcpf(1e-30f + bf_lo(sb.y)); v0[3] *= bf_hi(sa.y) * __builtin_amdgcn_rcpf(1e-30f + bf_hi(sb.y));
;                     v1[0] *= bf_lo(sa.z) * __builtin_amdgcn_rcpf(1e-30f + bf_lo(sb.z)); v1[1] *= bf_hi(sa.z) * __builtin_amdgcn_rcpf(1e-30f + bf_hi(sb.z));
;                     v1[2] *= bf_lo(sa.w) * __builtin_amdgcn_rcpf(1e-30f + bf_lo(sb.w)); v1[3] *= bf_hi(sa.w) * __builtin_amdgcn_rcpf(1e-30f + bf_hi(sb.w)); }
;                 asm volatile("" ::: "memory"); }
	v_lshlrev_b32_e32 v158, 16, v130
	v_and_b32_e32 v159, 0xffff0000, v130
	v_lshlrev_b32_e32 v136, 16, v154
	v_and_b32_e32 v137, 0xffff0000, v154
	v_lshlrev_b32_e32 v250, 16, v131
	v_and_b32_e32 v251, 0xffff0000, v131
	v_lshlrev_b32_e32 v252, 16, v155
	v_and_b32_e32 v253, 0xffff0000, v155
	v_add_f32_e32 v136, 0xda24260, v136
	v_add_f32_e32 v137, 0xda24260, v137
	v_add_f32_e32 v252, 0xda24260, v252
	v_add_f32_e32 v253, 0xda24260, v253
	v_rcp_f32_e32 v136, v136
	v_rcp_f32_e32 v137, v137
	v_rcp_f32_e32 v252, v252
	v_rcp_f32_e32 v253, v253
	v_pk_mul_f32 v[136:137], v[136:137], v[158:159]
	v_pk_mul_f32 v[252:253], v[252:253], v[250:251]
	v_pk_mul_f32 v[78:79], v[78:79], v[136:137]
	v_pk_mul_f32 v[80:81], v[80:81], v[252:253]
	v_lshlrev_b32_e32 v158, 16, v132
	v_and_b32_e32 v159, 0xffff0000, v132
	v_lshlrev_b32_e32 v136, 16, v156
	v_and_b32_e32 v137, 0xffff0000, v156
	v_lshlrev_b32_e32 v250, 16, v133
	v_and_b32_e32 v251, 0xffff0000, v133
	v_lshlrev_b32_e32 v252, 16, v157
	v_and_b32_e32 v253, 0xffff0000, v157
	v_add_f32_e32 v136, 0xda24260, v136
	v_add_f32_e32 v137, 0xda24260, v137
	v_add_f32_e32 v252, 0xda24260, v252
	v_add_f32_e32 v253, 0xda24260, v253
	v_rcp_f32_e32 v136, v136
	v_rcp_f32_e32 v137, v137
	v_rcp_f32_e32 v252, v252
	v_rcp_f32_e32 v253, v253
	v_pk_mul_f32 v[136:137], v[136:137], v[158:159]
	v_pk_mul_f32 v[252:253], v[252:253], v[250:251]
	v_pk_mul_f32 v[74:75], v[74:75], v[136:137]
	v_pk_mul_f32 v[76:77], v[76:77], v[252:253]
	global_load_dwordx4 v[130:133], v[134:135], off offset:256
	global_load_dwordx4 v[154:157], v[134:135], off offset:2304
	s_waitcnt vmcnt(4)
	v_lshlrev_b32_e32 v158, 16, v234
	v_and_b32_e32 v159, 0xffff0000, v234
	v_lshlrev_b32_e32 v136, 16, v242
	v_and_b32_e32 v137, 0xffff0000, v242
	v_lshlrev_b32_e32 v250, 16, v235
	v_and_b32_e32 v251, 0xffff0000, v235
	v_lshlrev_b32_e32 v252, 16, v243
	v_and_b32_e32 v253, 0xffff0000, v243
	v_add_f32_e32 v136, 0xda24260, v136
	v_add_f32_e32 v137, 0xda24260, v137
	v_add_f32_e32 v252, 0xda24260, v252
	v_add_f32_e32 v253, 0xda24260, v253
	v_rcp_f32_e32 v136, v136
	v_rcp_f32_e32 v137, v137
	v_rcp_f32_e32 v252, v252
	v_rcp_f32_e32 v253, v253
	v_pk_mul_f32 v[136:137], v[136:137], v[158:159]
	v_pk_mul_f32 v[252:253], v[252:253], v[250:251]
	v_pk_mul_f32 v[70:71], v[70:71], v[136:137]
	v_pk_mul_f32 v[72:73], v[72:73], v[252:253]
	v_lshlrev_b32_e32 v158, 16, v236
	v_and_b32_e32 v159, 0xffff0000, v236
	v_lshlrev_b32_e32 v136, 16, v244
	v_and_b32_e32 v137, 0xffff0000, v244
	v_lshlrev_b32_e32 v250, 16, v237
	v_and_b32_e32 v251, 0xffff0000, v237
	v_lshlrev_b32_e32 v252, 16, v245
	v_and_b32_e32 v253, 0xffff0000, v245
	v_add_f32_e32 v136, 0xda24260, v136
	v_add_f32_e32 v137, 0xda24260, v137
	v_add_f32_e32 v252, 0xda24260, v252
	v_add_f32_e32 v253, 0xda24260, v253
	v_rcp_f32_e32 v136, v136
	v_rcp_f32_e32 v137, v137
	v_rcp_f32_e32 v252, v252
	v_rcp_f32_e32 v253, v253
	v_pk_mul_f32 v[136:137], v[136:137], v[158:159]
	v_pk_mul_f32 v[252:253], v[252:253], v[250:251]
	v_pk_mul_f32 v[66:67], v[66:67], v[136:137]
	v_pk_mul_f32 v[68:69], v[68:69], v[252:253]
	v_add_co_u32_e32 v134, vcc, 0x10000, v134
	s_nop 1
	v_addc_co_u32_e32 v135, vcc, 0, v135, vcc
	global_load_dwordx4 v[234:237], v[134:135], off
	global_load_dwordx4 v[242:245], v[134:135], off offset:2048
	s_waitcnt vmcnt(4)
	v_lshlrev_b32_e32 v158, 16, v238
	v_and_b32_e32 v159, 0xffff0000, v238
	v_lshlrev_b32_e32 v136, 16, v246
	v_and_b32_e32 v137, 0xffff0000, v246
	v_lshlrev_b32_e32 v250, 16, v239
	v_and_b32_e32 v251, 0xffff0000, v239
	v_lshlrev_b32_e32 v252, 16, v247
	v_and_b32_e32 v253, 0xffff0000, v247
	v_add_f32_e32 v136, 0xda24260, v136
	v_add_f32_e32 v137, 0xda24260, v137
	v_add_f32_e32 v252, 0xda24260, v252
	v_add_f32_e32 v253, 0xda24260, v253
	v_rcp_f32_e32 v136, v136
	v_rcp_f32_e32 v137, v137
	v_rcp_f32_e32 v252, v252
	v_rcp_f32_e32 v253, v253
	v_pk_mul_f32 v[136:137], v[136:137], v[158:159]
	v_pk_mul_f32 v[252:253], v[252:253], v[250:251]
	v_pk_mul_f32 v[62:63], v[62:63], v[136:137]
	v_pk_mul_f32 v[64:65], v[64:65], v[252:253]
	v_lshlrev_b32_e32 v158, 16, v240
	v_and_b32_e32 v159, 0xffff0000, v240
	v_lshlrev_b32_e32 v136, 16, v248
	v_and_b32_e32 v137, 0xffff0000, v248
	v_lshlrev_b32_e32 v250, 16, v241
	v_and_b32_e32 v251, 0xffff0000, v241
	v_lshlrev_b32_e32 v252, 16, v249
	v_and_b32_e32 v253, 0xffff0000, v249
	v_add_f32_e32 v136, 0xda24260, v136
	v_add_f32_e32 v137, 0xda24260, v137
	v_add_f32_e32 v252, 0xda24260, v252
	v_add_f32_e32 v253, 0xda24260, v253
	v_rcp_f32_e32 v136, v136
	v_rcp_f32_e32 v137, v137
	v_rcp_f32_e32 v252, v252
	v_rcp_f32_e32 v253, v253
	v_pk_mul_f32 v[136:137], v[136:137], v[158:159]
	v_pk_mul_f32 v[252:253], v[252:253], v[250:251]
	v_pk_mul_f32 v[58:59], v[58:59], v[136:137]
	v_pk_mul_f32 v[60:61], v[60:61], v[252:253]
	global_load_dwordx4 v[238:241], v[134:135], off offset:256
	global_load_dwordx4 v[246:249], v[134:135], off offset:2304
	s_waitcnt vmcnt(4)
; __device__ __forceinline__ int otid() { int t = (int)threadIdx.x; asm volatile("" : "+v"(t)); return t; }
;     __device__ __forceinline__ void mid(f32x4 (&acc)[2][2][4][2], const Unit& u, int wr, int wc) const {
;         const int ln_ = otid() & 63, fr = ln_ & 15, fq = ln_ >> 4;
;         const size_t rowb = (size_t)u.pm * BM + wr * 64 + fr; const int col0 = u.pn * BM + wc * 32 + 8 * fq;
; #pragma unroll
;         for (int ai = 0; ai < 2; ++ai)
; #pragma unroll
;             for (int m = 0; m < 4; ++m) { const bf16_t* sp = SIG + (rowb + ai * HALF + m * 16) * 2048 + col0;
; #pragma unroll
;                 for (int bj = 0; bj < 2; ++bj) { const u32x4 sa = *(const u32x4*)(sp + bj * HALF), sb = *(const u32x4*)(sp + 1024 + bj * HALF);
;                     f32x4& v0 = acc[ai][bj][m][0]; f32x4& v1 = acc[ai][bj][m][1];
;                     v0[0] *= bf_lo(sa.x) * __builtin_amdgcn_rcpf(1e-30f + bf_lo(sb.x)); v0[1] *= bf_hi(sa.x) * __builtin_amdgcn_rcpf(1e-30f + bf_hi(sb.x));
;                     v0[2] *= bf_lo(sa.y) * __builtin_amdgcn_rcpf(1e-30f + bf_lo(sb.y)); v0[3] *= bf_hi(sa.y) * __builtin_amdgcn_rcpf(1e-30f + bf_hi(sb.y));
;                     v1[0] *= bf_lo(sa.z) * __builtin_amdgcn_rcpf(1e-30f + bf_lo(sb.z)); v1[1] *= bf_hi(sa.z) * __builtin_amdgcn_rcpf(1e-30f + bf_hi(sb.z));
;                     v1[2] *= bf_lo(sa.w) * __builtin_amdgcn_rcpf(1e-30f + bf_lo(sb.w)); v1[3] *= bf_hi(sa.w) * __builtin_amdgcn_rcpf(1e-30f + bf_hi(sb.w)); }
;                 asm volatile("" ::: "memory"); }
	v_lshlrev_b32_e32 v158, 16, v130
	v_and_b32_e32 v159, 0xffff0000, v130
	v_lshlrev_b32_e32 v136, 16, v154
	v_and_b32_e32 v137, 0xffff0000, v154
	v_lshlrev_b32_e32 v250, 16, v131
	v_and_b32_e32 v251, 0xffff0000, v131
	v_lshlrev_b32_e32 v252, 16, v155
	v_and_b32_e32 v253, 0xffff0000, v155
	v_add_f32_e32 v136, 0xda24260, v136
	v_add_f32_e32 v137, 0xda24260, v137
	v_add_f32_e32 v252, 0xda24260, v252
	v_add_f32_e32 v253, 0xda24260, v253
	v_rcp_f32_e32 v136, v136
	v_rcp_f32_e32 v137, v137
	v_rcp_f32_e32 v252, v252
	v_rcp_f32_e32 v253, v253
	v_pk_mul_f32 v[136:137], v[136:137], v[158:159]
	v_pk_mul_f32 v[252:253], v[252:253], v[250:251]
	v_pk_mul_f32 v[54:55], v[54:55], v[136:137]
	v_pk_mul_f32 v[56:57], v[56:57], v[252:253]
	v_lshlrev_b32_e32 v158, 16, v132
	v_and_b32_e32 v159, 0xffff0000, v132
	v_lshlrev_b32_e32 v136, 16, v156
	v_and_b32_e32 v137, 0xffff0000, v156
	v_lshlrev_b32_e32 v250, 16, v133
	v_and_b32_e32 v251, 0xffff0000, v133
	v_lshlrev_b32_e32 v252, 16, v157
	v_and_b32_e32 v253, 0xffff0000, v157
	v_add_f32_e32 v136, 0xda24260, v136
	v_add_f32_e32 v137, 0xda24260, v137
	v_add_f32_e32 v252, 0xda24260, v252
	v_add_f32_e32 v253, 0xda24260, v253
	v_rcp_f32_e32 v136, v136
	v_rcp_f32_e32 v137, v137
	v_rcp_f32_e32 v252, v252
	v_rcp_f32_e32 v253, v253
	v_pk_mul_f32 v[136:137], v[136:137], v[158:159]
	v_pk_mul_f32 v[252:253], v[252:253], v[250:251]
	v_pk_mul_f32 v[50:51], v[50:51], v[136:137]
	v_pk_mul_f32 v[52:53], v[52:53], v[252:253]
	v_add_co_u32_e32 v134, vcc, 0x10000, v134
	s_nop 1
	v_addc_co_u32_e32 v135, vcc, 0, v135, vcc
	global_load_dwordx4 v[130:133], v[134:135], off
	global_load_dwordx4 v[154:157], v[134:135], off offset:2048
	s_waitcnt vmcnt(4)
	v_lshlrev_b32_e32 v158, 16, v234
	v_and_b32_e32 v159, 0xffff0000, v234
	v_lshlrev_b32_e32 v136, 16, v242
	v_and_b32_e32 v137, 0xffff0000, v242
	v_lshlrev_b32_e32 v250, 16, v235
	v_and_b32_e32 v251, 0xffff0000, v235
	v_lshlrev_b32_e32 v252, 16, v243
	v_and_b32_e32 v253, 0xffff0000, v243
	v_add_f32_e32 v136, 0xda24260, v136
	v_add_f32_e32 v137, 0xda24260, v137
	v_add_f32_e32 v252, 0xda24260, v252
	v_add_f32_e32 v253, 0xda24260, v253
	v_rcp_f32_e32 v136, v136
	v_rcp_f32_e32 v137, v137
	v_rcp_f32_e32 v252, v252
	v_rcp_f32_e32 v253, v253
	v_pk_mul_f32 v[136:137], v[136:137], v[158:159]
	v_pk_mul_f32 v[252:253], v[252:253], v[250:251]
	v_pk_mul_f32 v[46:47], v[46:47], v[136:137]
	v_pk_mul_f32 v[48:49], v[48:49], v[252:253]
	v_lshlrev_b32_e32 v158, 16, v236
	v_and_b32_e32 v159, 0xffff0000, v236
	v_lshlrev_b32_e32 v136, 16, v244
	v_and_b32_e32 v137, 0xffff0000, v244
	v_lshlrev_b32_e32 v250, 16, v237
	v_and_b32_e32 v251, 0xffff0000, v237
	v_lshlrev_b32_e32 v252, 16, v245
	v_and_b32_e32 v253, 0xffff0000, v245
	v_add_f32_e32 v136, 0xda24260, v136
	v_add_f32_e32 v137, 0xda24260, v137
	v_add_f32_e32 v252, 0xda24260, v252
	v_add_f32_e32 v253, 0xda24260, v253
	v_rcp_f32_e32 v136, v136
	v_rcp_f32_e32 v137, v137
	v_rcp_f32_e32 v252, v252
	v_rcp_f32_e32 v253, v253
	v_pk_mul_f32 v[136:137], v[136:137], v[158:159]
	v_pk_mul_f32 v[252:253], v[252:253], v[250:251]
	v_pk_mul_f32 v[42:43], v[42:43], v[136:137]
	v_pk_mul_f32 v[44:45], v[44:45], v[252:253]
	global_load_dwordx4 v[234:237], v[134:135], off offset:256
	global_load_dwordx4 v[242:245], v[134:135], off offset:2304
	s_waitcnt vmcnt(4)
	v_lshlrev_b32_e32 v158, 16, v238
	v_and_b32_e32 v159, 0xffff0000, v238
	v_lshlrev_b32_e32 v136, 16, v246
	v_and_b32_e32 v137, 0xffff0000, v246
	v_lshlrev_b32_e32 v250, 16, v239
	v_and_b32_e32 v251, 0xffff0000, v239
	v_lshlrev_b32_e32 v252, 16, v247
	v_and_b32_e32 v253, 0xffff0000, v247
	v_add_f32_e32 v136, 0xda24260, v136
	v_add_f32_e32 v137, 0xda24260, v137
	v_add_f32_e32 v252, 0xda24260, v252
	v_add_f32_e32 v253, 0xda24260, v253
	v_rcp_f32_e32 v136, v136
	v_rcp_f32_e32 v137, v137
	v_rcp_f32_e32 v252, v252
	v_rcp_f32_e32 v253, v253
	v_pk_mul_f32 v[136:137], v[136:137], v[158:159]
	v_pk_mul_f32 v[252:253], v[252:253], v[250:251]
	v_pk_mul_f32 v[38:39], v[38:39], v[136:137]
	v_pk_mul_f32 v[40:41], v[40:41], v[252:253]
	v_lshlrev_b32_e32 v158, 16, v240
	v_and_b32_e32 v159, 0xffff0000, v240
	v_lshlrev_b32_e32 v136, 16, v248
	v_and_b32_e32 v137, 0xffff0000, v248
	v_lshlrev_b32_e32 v250, 16, v241
	v_and_b32_e32 v251, 0xffff0000, v241
	v_lshlrev_b32_e32 v252, 16, v249
	v_and_b32_e32 v253, 0xffff0000, v249
	v_add_f32_e32 v136, 0xda24260, v136
	v_add_f32_e32 v137, 0xda24260, v137
	v_add_f32_e32 v252, 0xda24260, v252
	v_add_f32_e32 v253, 0xda24260, v253
	v_rcp_f32_e32 v136, v136
	v_rcp_f32_e32 v137, v137
	v_rcp_f32_e32 v252, v252
	v_rcp_f32_e32 v253, v253
	v_pk_mul_f32 v[136:137], v[136:137], v[158:159]
	v_pk_mul_f32 v[252:253], v[252:253], v[250:251]
	v_pk_mul_f32 v[34:35], v[34:35], v[136:137]
	v_pk_mul_f32 v[36:37], v[36:37], v[252:253]
	v_add_co_u32_e32 v134, vcc, 0x10000, v134
	s_nop 1
	v_addc_co_u32_e32 v135, vcc, 0, v135, vcc
	global_load_dwordx4 v[238:241], v[134:135], off
	global_load_dwordx4 v[246:249], v[134:135], off offset:2048
	s_waitcnt vmcnt(4)
;     __device__ __forceinline__ void mid(f32x4 (&acc)[2][2][4][2], const Unit& u, int wr, int wc) const {
;     ...
;             for (int m = 0; m < 4; ++m) { const bf16_t* sp = SIG + (rowb + ai * HALF + m * 16) * 2048 + col0;
; #pragma unroll
;                 for (int bj = 0; bj < 2; ++bj) { const u32x4 sa = *(const u32x4*)(sp + bj * HALF), sb = *(const u32x4*)(sp + 1024 + bj * HALF);
;                     f32x4& v0 = acc[ai][bj][m][0]; f32x4& v1 = acc[ai][bj][m][1];
;                     v0[0] *= bf_lo(sa.x) * __builtin_amdgcn_rcpf(1e-30f + bf_lo(sb.x)); v0[1] *= bf_hi(sa.x) * __builtin_amdgcn_rcpf(1e-30f + bf_hi(sb.x));
;                     v0[2] *= bf_lo(sa.y) * __builtin_amdgcn_rcpf(1e-30f + bf_lo(sb.y)); v0[3] *= bf_hi(sa.y) * __builtin_amdgcn_rcpf(1e-30f + bf_hi(sb.y));
;                     v1[0] *= bf_lo(sa.z) * __builtin_amdgcn_rcpf(1e-30f + bf_lo(sb.z)); v1[1] *= bf_hi(sa.z) * __builtin_amdgcn_rcpf(1e-30f + bf_hi(sb.z));
;                     v1[2] *= bf_lo(sa.w) * __builtin_amdgcn_rcpf(1e-30f + bf_lo(sb.w)); v1[3] *= bf_hi(sa.w) * __builtin_amdgcn_rcpf(1e-30f + bf_hi(sb.w)); }
	v_lshlrev_b32_e32 v158, 16, v130
	v_and_b32_e32 v159, 0xffff0000, v130
	v_lshlrev_b32_e32 v136, 16, v154
	v_and_b32_e32 v137, 0xffff0000, v154
	v_lshlrev_b32_e32 v250, 16, v131
	v_and_b32_e32 v251, 0xffff0000, v131
	v_lshlrev_b32_e32 v252, 16, v155
	v_and_b32_e32 v253, 0xffff0000, v155
	v_add_f32_e32 v136, 0xda24260, v136
	v_add_f32_e32 v137, 0xda24260, v137
	v_add_f32_e32 v252, 0xda24260, v252
	v_add_f32_e32 v253, 0xda24260, v253
	v_rcp_f32_e32 v136, v136
	v_rcp_f32_e32 v137, v137
	v_rcp_f32_e32 v252, v252
	v_rcp_f32_e32 v253, v253
	v_pk_mul_f32 v[136:137], v[136:137], v[158:159]
	v_pk_mul_f32 v[252:253], v[252:253], v[250:251]
	v_pk_mul_f32 v[30:31], v[30:31], v[136:137]
	v_pk_mul_f32 v[32:33], v[32:33], v[252:253]
	v_lshlrev_b32_e32 v158, 16, v132
	v_and_b32_e32 v159, 0xffff0000, v132
	v_lshlrev_b32_e32 v136, 16, v156
	v_and_b32_e32 v137, 0xffff0000, v156
	v_lshlrev_b32_e32 v250, 16, v133
	v_and_b32_e32 v251, 0xffff0000, v133
	v_lshlrev_b32_e32 v252, 16, v157
	v_and_b32_e32 v253, 0xffff0000, v157
	v_add_f32_e32 v136, 0xda24260, v136
	v_add_f32_e32 v137, 0xda24260, v137
	v_add_f32_e32 v252, 0xda24260, v252
	v_add_f32_e32 v253, 0xda24260, v253
	v_rcp_f32_e32 v136, v136
	v_rcp_f32_e32 v137, v137
	v_rcp_f32_e32 v252, v252
	v_rcp_f32_e32 v253, v253
	v_pk_mul_f32 v[136:137], v[136:137], v[158:159]
	v_pk_mul_f32 v[252:253], v[252:253], v[250:251]
	v_pk_mul_f32 v[26:27], v[26:27], v[136:137]
	v_pk_mul_f32 v[28:29], v[28:29], v[252:253]
	global_load_dwordx4 v[130:133], v[134:135], off offset:256
	global_load_dwordx4 v[154:157], v[134:135], off offset:2304
	s_waitcnt vmcnt(4)
	v_lshlrev_b32_e32 v158, 16, v234
	v_and_b32_e32 v159, 0xffff0000, v234
	v_lshlrev_b32_e32 v136, 16, v242
	v_and_b32_e32 v137, 0xffff0000, v242
	v_lshlrev_b32_e32 v250, 16, v235
	v_and_b32_e32 v251, 0xffff0000, v235
	v_lshlrev_b32_e32 v252, 16, v243
	v_and_b32_e32 v253, 0xffff0000, v243
	v_add_f32_e32 v136, 0xda24260, v136
	v_add_f32_e32 v137, 0xda24260, v137
	v_add_f32_e32 v252, 0xda24260, v252
	v_add_f32_e32 v253, 0xda24260, v253
	v_rcp_f32_e32 v136, v136
	v_rcp_f32_e32 v137, v137
	v_rcp_f32_e32 v252, v252
	v_rcp_f32_e32 v253, v253
	v_pk_mul_f32 v[136:137], v[136:137], v[158:159]
	v_pk_mul_f32 v[252:253], v[252:253], v[250:251]
	v_pk_mul_f32 v[22:23], v[22:23], v[136:137]
	v_pk_mul_f32 v[24:25], v[24:25], v[252:253]
	v_lshlrev_b32_e32 v158, 16, v236
	v_and_b32_e32 v159, 0xffff0000, v236
	v_lshlrev_b32_e32 v136, 16, v244
	v_and_b32_e32 v137, 0xffff0000, v244
	v_lshlrev_b32_e32 v250, 16, v237
	v_and_b32_e32 v251, 0xffff0000, v237
	v_lshlrev_b32_e32 v252, 16, v245
	v_and_b32_e32 v253, 0xffff0000, v245
	v_add_f32_e32 v136, 0xda24260, v136
	v_add_f32_e32 v137, 0xda24260, v137
	v_add_f32_e32 v252, 0xda24260, v252
	v_add_f32_e32 v253, 0xda24260, v253
	v_rcp_f32_e32 v136, v136
	v_rcp_f32_e32 v137, v137
	v_rcp_f32_e32 v252, v252
	v_rcp_f32_e32 v253, v253
	v_pk_mul_f32 v[136:137], v[136:137], v[158:159]
	v_pk_mul_f32 v[252:253], v[252:253], v[250:251]
	v_pk_mul_f32 v[18:19], v[18:19], v[136:137]
	v_pk_mul_f32 v[20:21], v[20:21], v[252:253]
	s_waitcnt vmcnt(2)
	v_lshlrev_b32_e32 v158, 16, v238
	v_and_b32_e32 v159, 0xffff0000, v238
	v_lshlrev_b32_e32 v136, 16, v246
	v_and_b32_e32 v137, 0xffff0000, v246
	v_lshlrev_b32_e32 v250, 16, v239
	v_and_b32_e32 v251, 0xffff0000, v239
	v_lshlrev_b32_e32 v252, 16, v247
	v_and_b32_e32 v253, 0xffff0000, v247
	v_add_f32_e32 v136, 0xda24260, v136
	v_add_f32_e32 v137, 0xda24260, v137
	v_add_f32_e32 v252, 0xda24260, v252
	v_add_f32_e32 v253, 0xda24260, v253
	v_rcp_f32_e32 v136, v136
	v_rcp_f32_e32 v137, v137
	v_rcp_f32_e32 v252, v252
	v_rcp_f32_e32 v253, v253
	v_pk_mul_f32 v[136:137], v[136:137], v[158:159]
	v_pk_mul_f32 v[252:253], v[252:253], v[250:251]
	v_pk_mul_f32 v[14:15], v[14:15], v[136:137]
	v_pk_mul_f32 v[16:17], v[16:17], v[252:253]
	v_lshlrev_b32_e32 v158, 16, v240
	v_and_b32_e32 v159, 0xffff0000, v240
	v_lshlrev_b32_e32 v136, 16, v248
	v_and_b32_e32 v137, 0xffff0000, v248
	v_lshlrev_b32_e32 v250, 16, v241
	v_and_b32_e32 v251, 0xffff0000, v241
	v_lshlrev_b32_e32 v252, 16, v249
	v_and_b32_e32 v253, 0xffff0000, v249
	v_add_f32_e32 v136, 0xda24260, v136
	v_add_f32_e32 v137, 0xda24260, v137
	v_add_f32_e32 v252, 0xda24260, v252
	v_add_f32_e32 v253, 0xda24260, v253
	v_rcp_f32_e32 v136, v136
	v_rcp_f32_e32 v137, v137
	v_rcp_f32_e32 v252, v252
	v_rcp_f32_e32 v253, v253
	v_pk_mul_f32 v[136:137], v[136:137], v[158:159]
	v_pk_mul_f32 v[252:253], v[252:253], v[250:251]
	v_pk_mul_f32 v[10:11], v[10:11], v[136:137]
	v_pk_mul_f32 v[12:13], v[12:13], v[252:253]
	s_waitcnt vmcnt(0)
	v_lshlrev_b32_e32 v158, 16, v130
	v_and_b32_e32 v159, 0xffff0000, v130
	v_lshlrev_b32_e32 v136, 16, v154
	v_and_b32_e32 v137, 0xffff0000, v154
	v_lshlrev_b32_e32 v250, 16, v131
	v_and_b32_e32 v251, 0xffff0000, v131
	v_lshlrev_b32_e32 v252, 16, v155
	v_and_b32_e32 v253, 0xffff0000, v155
	v_add_f32_e32 v136, 0xda24260, v136
	v_add_f32_e32 v137, 0xda24260, v137
	v_add_f32_e32 v252, 0xda24260, v252
	v_add_f32_e32 v253, 0xda24260, v253
	v_rcp_f32_e32 v136, v136
	v_rcp_f32_e32 v137, v137
	v_rcp_f32_e32 v252, v252
	v_rcp_f32_e32 v253, v253
	v_pk_mul_f32 v[136:137], v[136:137], v[158:159]
	v_pk_mul_f32 v[252:253], v[252:253], v[250:251]
	v_pk_mul_f32 v[6:7], v[6:7], v[136:137]
	v_pk_mul_f32 v[8:9], v[8:9], v[252:253]
	v_lshlrev_b32_e32 v158, 16, v132
	v_and_b32_e32 v159, 0xffff0000, v132
	v_lshlrev_b32_e32 v136, 16, v156
	v_and_b32_e32 v137, 0xffff0000, v156
	v_lshlrev_b32_e32 v250, 16, v133
	v_and_b32_e32 v251, 0xffff0000, v133
	v_lshlrev_b32_e32 v252, 16, v157
	v_and_b32_e32 v253, 0xffff0000, v157
	v_add_f32_e32 v136, 0xda24260, v136
	v_add_f32_e32 v137, 0xda24260, v137
	v_add_f32_e32 v252, 0xda24260, v252
	v_add_f32_e32 v253, 0xda24260, v253
	v_rcp_f32_e32 v136, v136
	v_rcp_f32_e32 v137, v137
	v_rcp_f32_e32 v252, v252
	v_rcp_f32_e32 v253, v253
	v_pk_mul_f32 v[136:137], v[136:137], v[158:159]
	v_pk_mul_f32 v[252:253], v[252:253], v[250:251]
	v_pk_mul_f32 v[2:3], v[2:3], v[136:137]
	v_pk_mul_f32 v[4:5], v[4:5], v[252:253]
	s_mov_b64 s[8:9], 0xb0000
	s_branch .LBB0_212

; __device__ __forceinline__ int otid() { int t = (int)threadIdx.x; asm volatile("" : "+v"(t)); return t; }
; __device__ __forceinline__ unsigned cvt_pk_bf16(float lo, float hi) { unsigned r; asm volatile("v_cvt_pk_bf16_f32 %0, %1, %2" : "=v"(r) : "v"(lo), "v"(hi)); return r; }
;     __device__ __forceinline__ void operator()(const f32x4 (&acc)[2][2][4][2], const Unit& u, int wr, int wc, int fr, int fq) const {
;         { const int ln_ = otid() & 63; fr = ln_ & 15; fq = ln_ >> 4; }
;         const size_t rowb = (size_t)u.pm * BM + wr * 64 + fr; const int col0 = u.pn * BM + wc * 32 + 8 * fq;
; #pragma unroll
;         for (int ai = 0; ai < 2; ++ai)
; #pragma unroll
;             for (int m = 0; m < 4; ++m) { const size_t row = rowb + ai * HALF + m * 16;
; #pragma unroll
;                 for (int bj = 0; bj < 2; ++bj) { const u32x4 sg = *(const u32x4*)(SIG + row * 2048 + 1024 + col0 + bj * HALF);
;                     f32x4 v0 = acc[ai][bj][m][0], v1 = acc[ai][bj][m][1];
;                     v0[0] *= bf_lo(sg.x); v0[1] *= bf_hi(sg.x); v0[2] *= bf_lo(sg.y); v0[3] *= bf_hi(sg.y);
;                     v1[0] *= bf_lo(sg.z); v1[1] *= bf_hi(sg.z); v1[2] *= bf_lo(sg.w); v1[3] *= bf_hi(sg.w);
;                     u32x4 w; w.x = cvt_pk_bf16(v0[0], v0[1]); w.y = cvt_pk_bf16(v0[2], v0[3]); w.z = cvt_pk_bf16(v1[0], v1[1]); w.w = cvt_pk_bf16(v1[2], v1[3]);
;                     *(u32x4*)(O + row * 1024 + col0 + bj * HALF) = w; } }
.LBB0_217:
	v_mov_b32_e32 v130, v221
	s_lshl_b64 s[2:3], s[46:47], 8
	s_add_u32 s2, s2, s56
	v_and_or_b32 v132, v130, 15, s2
	v_lshrrev_b32_e32 v130, 1, v130
	s_addc_u32 s3, s3, s60
	v_and_or_b32 v130, v130, 24, s57
	v_mov_b32_e32 v133, s3
	v_or_b32_e32 v130, s17, v130
	v_ashrrev_i32_e32 v131, 31, v130
	v_lshlrev_b64 v[134:135], 12, v[132:133]
	v_lshl_add_u64 v[134:135], s[12:13], 0, v[134:135]
	v_lshlrev_b64 v[130:131], 1, v[130:131]
	v_lshl_add_u64 v[150:151], v[134:135], 0, v[130:131]
	v_lshlrev_b64 v[148:149], 11, v[132:133]
	v_lshl_add_u64 v[148:149], s[92:93], 0, v[148:149]
	v_lshl_add_u64 v[148:149], v[148:149], 0, v[130:131]
	global_load_dwordx4 v[234:237], v[150:151], off offset:2048
	global_load_dwordx4 v[238:241], v[150:151], off offset:2304
	v_add_co_u32_e32 v150, vcc, 0x10000, v150
	s_nop 1
	v_addc_co_u32_e32 v151, vcc, 0, v151, vcc
	global_load_dwordx4 v[242:245], v[150:151], off offset:2048
	global_load_dwordx4 v[246:249], v[150:151], off offset:2304
	v_add_co_u32_e32 v150, vcc, 0x10000, v150
	s_nop 1
	v_addc_co_u32_e32 v151, vcc, 0, v151, vcc
	global_load_dwordx4 v[134:137], v[150:151], off offset:2048
	s_waitcnt vmcnt(4)
	v_lshlrev_b32_e32 v250, 16, v234
	v_and_b32_e32 v251, 0xffff0000, v234
	v_mul_f32_e32 v126, v126, v250
	v_mul_f32_e32 v127, v127, v251
	v_lshlrev_b32_e32 v252, 16, v235
	v_and_b32_e32 v253, 0xffff0000, v235
	v_mul_f32_e32 v128, v128, v252
	v_mul_f32_e32 v129, v129, v253
	v_lshlrev_b32_e32 v250, 16, v236
	v_and_b32_e32 v251, 0xffff0000, v236
	v_mul_f32_e32 v122, v122, v250
	v_mul_f32_e32 v123, v123, v251
	v_lshlrev_b32_e32 v252, 16, v237
	v_and_b32_e32 v253, 0xffff0000, v237
	v_mul_f32_e32 v124, v124, v252
	v_mul_f32_e32 v125, v125, v253
	v_cvt_pk_bf16_f32 v234, v126, v127
	v_cvt_pk_bf16_f32 v235, v128, v129
	v_cvt_pk_bf16_f32 v236, v122, v123
	v_cvt_pk_bf16_f32 v237, v124, v125
	global_store_dwordx4 v[148:149], v[234:237], off
	global_load_dwordx4 v[234:237], v[150:151], off offset:2304
	s_waitcnt vmcnt(5)
	v_lshlrev_b32_e32 v250, 16, v238
	v_and_b32_e32 v251, 0xffff0000, v238
	v_mul_f32_e32 v118, v118, v250
	v_mul_f32_e32 v119, v119, v251
	v_lshlrev_b32_e32 v252, 16, v239
	v_and_b32_e32 v253, 0xffff0000, v239
	v_mul_f32_e32 v120, v120, v252
	v_mul_f32_e32 v121, v121, v253
	v_lshlrev_b32_e32 v250, 16, v240
	v_and_b32_e32 v251, 0xffff0000, v240
	v_mul_f32_e32 v114, v114, v250
	v_mul_f32_e32 v115, v115, v251
	v_lshlrev_b32_e32 v252, 16, v241
	v_and_b32_e32 v253, 0xffff0000, v241
	v_mul_f32_e32 v116, v116, v252
	v_mul_f32_e32 v117, v117, v253
	v_cvt_pk_bf16_f32 v238, v118, v119
	v_cvt_pk_bf16_f32 v239, v120, v121
	v_cvt_pk_bf16_f32 v240, v114, v115
	v_cvt_pk_bf16_f32 v241, v116, v117
	global_store_dwordx4 v[148:149], v[238:241], off offset:256
	v_add_co_u32_e32 v148, vcc, 0x8000, v148
	s_nop 1
	v_addc_co_u32_e32 v149, vcc, 0, v149, vcc
	v_add_co_u32_e32 v150, vcc, 0x10000, v150
	s_nop 1
	v_addc_co_u32_e32 v151, vcc, 0, v151, vcc
	global_load_dwordx4 v[238:241], v[150:151], off offset:2048
	s_waitcnt vmcnt(6)
	v_lshlrev_b32_e32 v250, 16, v242
	v_and_b32_e32 v251, 0xffff0000, v242
	v_mul_f32_e32 v110, v110, v250
	v_mul_f32_e32 v111, v111, v251
	v_lshlrev_b32_e32 v252, 16, v243
	v_and_b32_e32 v253, 0xffff0000, v243
	v_mul_f32_e32 v112, v112, v252
	v_mul_f32_e32 v113, v113, v253
	v_lshlrev_b32_e32 v250, 16, v244
	v_and_b32_e32 v251, 0xffff0000, v244
	v_mul_f32_e32 v106, v106, v250
	v_mul_f32_e32 v107, v107, v251
	v_lshlrev_b32_e32 v252, 16, v245
	v_and_b32_e32 v253, 0xffff0000, v245
	v_mul_f32_e32 v108, v108, v252
	v_mul_f32_e32 v109, v109, v253
	v_cvt_pk_bf16_f32 v242, v110, v111
	v_cvt_pk_bf16_f32 v243, v112, v113
	v_cvt_pk_bf16_f32 v244, v106, v107
	v_cvt_pk_bf16_f32 v245, v108, v109
	global_store_dwordx4 v[148:149], v[242:245], off
	global_load_dwordx4 v[242:245], v[150:151], off offset:2304
	s_waitcnt vmcnt(7)
	v_lshlrev_b32_e32 v250, 16, v246
	v_and_b32_e32 v251, 0xffff0000, v246
	v_mul_f32_e32 v102, v102, v250
	v_mul_f32_e32 v103, v103, v251
	v_lshlrev_b32_e32 v252, 16, v247
	v_and_b32_e32 v253, 0xffff0000, v247
	v_mul_f32_e32 v104, v104, v252
	v_mul_f32_e32 v105, v105, v253
	v_lshlrev_b32_e32 v250, 16, v248
	v_and_b32_e32 v251, 0xffff0000, v248
	v_mul_f32_e32 v98, v98, v250
	v_mul_f32_e32 v99, v99, v251
	v_lshlrev_b32_e32 v252, 16, v249
	v_and_b32_e32 v253, 0xffff0000, v249
	v_mul_f32_e32 v100, v100, v252
	v_mul_f32_e32 v101, v101, v253
	v_cvt_pk_bf16_f32 v246, v102, v103
	v_cvt_pk_bf16_f32 v247, v104, v105
	v_cvt_pk_bf16_f32 v248, v98, v99
	v_cvt_pk_bf16_f32 v249, v100, v101
	global_store_dwordx4 v[148:149], v[246:249], off offset:256
	v_add_co_u32_e32 v148, vcc, 0x8000, v148
	s_nop 1
	v_addc_co_u32_e32 v149, vcc, 0, v149, vcc
	v_add_co_u32_e32 v150, vcc, 0x50000, v150
	s_nop 1
	v_addc_co_u32_e32 v151, vcc, 0, v151, vcc
	global_load_dwordx4 v[246:249], v[150:151], off offset:2048
	s_waitcnt vmcnt(8)
	v_lshlrev_b32_e32 v250, 16, v134
	v_and_b32_e32 v251, 0xffff0000, v134
	v_mul_f32_e32 v94, v94, v250
	v_mul_f32_e32 v95, v95, v251
	v_lshlrev_b32_e32 v252, 16, v135
	v_and_b32_e32 v253, 0xffff0000, v135
	v_mul_f32_e32 v96, v96, v252
	v_mul_f32_e32 v97, v97, v253
	v_lshlrev_b32_e32 v250, 16, v136
	v_and_b32_e32 v251, 0xffff0000, v136
	v_mul_f32_e32 v90, v90, v250
	v_mul_f32_e32 v91, v91, v251
	v_lshlrev_b32_e32 v252, 16, v137
	v_and_b32_e32 v253, 0xffff0000, v137
	v_mul_f32_e32 v92, v92, v252
	v_mul_f32_e32 v93, v93, v253
	v_cvt_pk_bf16_f32 v134, v94, v95
	v_cvt_pk_bf16_f32 v135, v96, v97
	v_cvt_pk_bf16_f32 v136, v90, v91
	v_cvt_pk_bf16_f32 v137, v92, v93
	global_store_dwordx4 v[148:149], v[134:137], off
	global_load_dwordx4 v[134:137], v[150:151], off offset:2304
	s_waitcnt vmcnt(8)
; __device__ __forceinline__ unsigned cvt_pk_bf16(float lo, float hi) { unsigned r; asm volatile("v_cvt_pk_bf16_f32 %0, %1, %2" : "=v"(r) : "v"(lo), "v"(hi)); return r; }
;     __device__ __forceinline__ void operator()(const f32x4 (&acc)[2][2][4][2], const Unit& u, int wr, int wc, int fr, int fq) const {
;     ...
;             for (int m = 0; m < 4; ++m) { const size_t row = rowb + ai * HALF + m * 16;
; #pragma unroll
;                 for (int bj = 0; bj < 2; ++bj) { const u32x4 sg = *(const u32x4*)(SIG + row * 2048 + 1024 + col0 + bj * HALF);
;                     f32x4 v0 = acc[ai][bj][m][0], v1 = acc[ai][bj][m][1];
;                     v0[0] *= bf_lo(sg.x); v0[1] *= bf_hi(sg.x); v0[2] *= bf_lo(sg.y); v0[3] *= bf_hi(sg.y);
;                     v1[0] *= bf_lo(sg.z); v1[1] *= bf_hi(sg.z); v1[2] *= bf_lo(sg.w); v1[3] *= bf_hi(sg.w);
;                     u32x4 w; w.x = cvt_pk_bf16(v0[0], v0[1]); w.y = cvt_pk_bf16(v0[2], v0[3]); w.z = cvt_pk_bf16(v1[0], v1[1]); w.w = cvt_pk_bf16(v1[2], v1[3]);
;                     *(u32x4*)(O + row * 1024 + col0 + bj * HALF) = w; } }
	v_lshlrev_b32_e32 v250, 16, v234
	v_and_b32_e32 v251, 0xffff0000, v234
	v_mul_f32_e32 v86, v86, v250
	v_mul_f32_e32 v87, v87, v251
	v_lshlrev_b32_e32 v252, 16, v235
	v_and_b32_e32 v253, 0xffff0000, v235
	v_mul_f32_e32 v88, v88, v252
	v_mul_f32_e32 v89, v89, v253
	v_lshlrev_b32_e32 v250, 16, v236
	v_and_b32_e32 v251, 0xffff0000, v236
	v_mul_f32_e32 v82, v82, v250
	v_mul_f32_e32 v83, v83, v251
	v_lshlrev_b32_e32 v252, 16, v237
	v_and_b32_e32 v253, 0xffff0000, v237
	v_mul_f32_e32 v84, v84, v252
	v_mul_f32_e32 v85, v85, v253
	v_cvt_pk_bf16_f32 v234, v86, v87
	v_cvt_pk_bf16_f32 v235, v88, v89
	v_cvt_pk_bf16_f32 v236, v82, v83
	v_cvt_pk_bf16_f32 v237, v84, v85
	global_store_dwordx4 v[148:149], v[234:237], off offset:256
	v_add_co_u32_e32 v148, vcc, 0x8000, v148
	s_nop 1
	v_addc_co_u32_e32 v149, vcc, 0, v149, vcc
	v_add_co_u32_e32 v150, vcc, 0x10000, v150
	s_nop 1
	v_addc_co_u32_e32 v151, vcc, 0, v151, vcc
	global_load_dwordx4 v[234:237], v[150:151], off offset:2048
	s_waitcnt vmcnt(8)
	v_lshlrev_b32_e32 v250, 16, v238
	v_and_b32_e32 v251, 0xffff0000, v238
	v_mul_f32_e32 v78, v78, v250
	v_mul_f32_e32 v79, v79, v251
	v_lshlrev_b32_e32 v252, 16, v239
	v_and_b32_e32 v253, 0xffff0000, v239
	v_mul_f32_e32 v80, v80, v252
	v_mul_f32_e32 v81, v81, v253
	v_lshlrev_b32_e32 v250, 16, v240
	v_and_b32_e32 v251, 0xffff0000, v240
	v_mul_f32_e32 v74, v74, v250
	v_mul_f32_e32 v75, v75, v251
	v_lshlrev_b32_e32 v252, 16, v241
	v_and_b32_e32 v253, 0xffff0000, v241
	v_mul_f32_e32 v76, v76, v252
	v_mul_f32_e32 v77, v77, v253
	v_cvt_pk_bf16_f32 v238, v78, v79
	v_cvt_pk_bf16_f32 v239, v80, v81
	v_cvt_pk_bf16_f32 v240, v74, v75
	v_cvt_pk_bf16_f32 v241, v76, v77
	global_store_dwordx4 v[148:149], v[238:241], off
	global_load_dwordx4 v[238:241], v[150:151], off offset:2304
	s_waitcnt vmcnt(8)
	v_lshlrev_b32_e32 v250, 16, v242
	v_and_b32_e32 v251, 0xffff0000, v242
	v_mul_f32_e32 v70, v70, v250
	v_mul_f32_e32 v71, v71, v251
	v_lshlrev_b32_e32 v252, 16, v243
	v_and_b32_e32 v253, 0xffff0000, v243
	v_mul_f32_e32 v72, v72, v252
	v_mul_f32_e32 v73, v73, v253
	v_lshlrev_b32_e32 v250, 16, v244
	v_and_b32_e32 v251, 0xffff0000, v244
	v_mul_f32_e32 v66, v66, v250
	v_mul_f32_e32 v67, v67, v251
	v_lshlrev_b32_e32 v252, 16, v245
	v_and_b32_e32 v253, 0xffff0000, v245
	v_mul_f32_e32 v68, v68, v252
	v_mul_f32_e32 v69, v69, v253
	v_cvt_pk_bf16_f32 v242, v70, v71
	v_cvt_pk_bf16_f32 v243, v72, v73
	v_cvt_pk_bf16_f32 v244, v66, v67
	v_cvt_pk_bf16_f32 v245, v68, v69
	global_store_dwordx4 v[148:149], v[242:245], off offset:256
	v_add_co_u32_e32 v148, vcc, 0x28000, v148
	s_nop 1
	v_addc_co_u32_e32 v149, vcc, 0, v149, vcc
	v_add_co_u32_e32 v150, vcc, 0x10000, v150
	s_nop 1
	v_addc_co_u32_e32 v151, vcc, 0, v151, vcc
	global_load_dwordx4 v[242:245], v[150:151], off offset:2048
	s_waitcnt vmcnt(8)
	v_lshlrev_b32_e32 v250, 16, v246
	v_and_b32_e32 v251, 0xffff0000, v246
	v_mul_f32_e32 v62, v62, v250
	v_mul_f32_e32 v63, v63, v251
	v_lshlrev_b32_e32 v252, 16, v247
	v_and_b32_e32 v253, 0xffff0000, v247
	v_mul_f32_e32 v64, v64, v252
	v_mul_f32_e32 v65, v65, v253
	v_lshlrev_b32_e32 v250, 16, v248
	v_and_b32_e32 v251, 0xffff0000, v248
	v_mul_f32_e32 v58, v58, v250
	v_mul_f32_e32 v59, v59, v251
	v_lshlrev_b32_e32 v252, 16, v249
	v_and_b32_e32 v253, 0xffff0000, v249
	v_mul_f32_e32 v60, v60, v252
	v_mul_f32_e32 v61, v61, v253
	v_cvt_pk_bf16_f32 v246, v62, v63
	v_cvt_pk_bf16_f32 v247, v64, v65
	v_cvt_pk_bf16_f32 v248, v58, v59
	v_cvt_pk_bf16_f32 v249, v60, v61
	global_store_dwordx4 v[148:149], v[246:249], off
	global_load_dwordx4 v[246:249], v[150:151], off offset:2304
	s_waitcnt vmcnt(8)
	v_lshlrev_b32_e32 v250, 16, v134
	v_and_b32_e32 v251, 0xffff0000, v134
	v_mul_f32_e32 v54, v54, v250
	v_mul_f32_e32 v55, v55, v251
	v_lshlrev_b32_e32 v252, 16, v135
	v_and_b32_e32 v253, 0xffff0000, v135
	v_mul_f32_e32 v56, v56, v252
	v_mul_f32_e32 v57, v57, v253
	v_lshlrev_b32_e32 v250, 16, v136
	v_and_b32_e32 v251, 0xffff0000, v136
	v_mul_f32_e32 v50, v50, v250
	v_mul_f32_e32 v51, v51, v251
	v_lshlrev_b32_e32 v252, 16, v137
	v_and_b32_e32 v253, 0xffff0000, v137
	v_mul_f32_e32 v52, v52, v252
	v_mul_f32_e32 v53, v53, v253
	v_cvt_pk_bf16_f32 v134, v54, v55
	v_cvt_pk_bf16_f32 v135, v56, v57
	v_cvt_pk_bf16_f32 v136, v50, v51
	v_cvt_pk_bf16_f32 v137, v52, v53
	global_store_dwordx4 v[148:149], v[134:137], off offset:256
	v_add_co_u32_e32 v148, vcc, 0x8000, v148
	s_nop 1
	v_addc_co_u32_e32 v149, vcc, 0, v149, vcc
	v_add_co_u32_e32 v150, vcc, 0x10000, v150
	s_nop 1
	v_addc_co_u32_e32 v151, vcc, 0, v151, vcc
	global_load_dwordx4 v[134:137], v[150:151], off offset:2048
	s_waitcnt vmcnt(8)
; __device__ __forceinline__ unsigned cvt_pk_bf16(float lo, float hi) { unsigned r; asm volatile("v_cvt_pk_bf16_f32 %0, %1, %2" : "=v"(r) : "v"(lo), "v"(hi)); return r; }
;     __device__ __forceinline__ void operator()(const f32x4 (&acc)[2][2][4][2], const Unit& u, int wr, int wc, int fr, int fq) const {
;     ...
;             for (int m = 0; m < 4; ++m) { const size_t row = rowb + ai * HALF + m * 16;
; #pragma unroll
;                 for (int bj = 0; bj < 2; ++bj) { const u32x4 sg = *(const u32x4*)(SIG + row * 2048 + 1024 + col0 + bj * HALF);
;                     f32x4 v0 = acc[ai][bj][m][0], v1 = acc[ai][bj][m][1];
;                     v0[0] *= bf_lo(sg.x); v0[1] *= bf_hi(sg.x); v0[2] *= bf_lo(sg.y); v0[3] *= bf_hi(sg.y);
;                     v1[0] *= bf_lo(sg.z); v1[1] *= bf_hi(sg.z); v1[2] *= bf_lo(sg.w); v1[3] *= bf_hi(sg.w);
;                     u32x4 w; w.x = cvt_pk_bf16(v0[0], v0[1]); w.y = cvt_pk_bf16(v0[2], v0[3]); w.z = cvt_pk_bf16(v1[0], v1[1]); w.w = cvt_pk_bf16(v1[2], v1[3]);
;                     *(u32x4*)(O + row * 1024 + col0 + bj * HALF) = w; } }
	v_lshlrev_b32_e32 v250, 16, v234
	v_and_b32_e32 v251, 0xffff0000, v234
	v_mul_f32_e32 v46, v46, v250
	v_mul_f32_e32 v47, v47, v251
	v_lshlrev_b32_e32 v252, 16, v235
	v_and_b32_e32 v253, 0xffff0000, v235
	v_mul_f32_e32 v48, v48, v252
	v_mul_f32_e32 v49, v49, v253
	v_lshlrev_b32_e32 v250, 16, v236
	v_and_b32_e32 v251, 0xffff0000, v236
	v_mul_f32_e32 v42, v42, v250
	v_mul_f32_e32 v43, v43, v251
	v_lshlrev_b32_e32 v252, 16, v237
	v_and_b32_e32 v253, 0xffff0000, v237
	v_mul_f32_e32 v44, v44, v252
	v_mul_f32_e32 v45, v45, v253
	v_cvt_pk_bf16_f32 v234, v46, v47
	v_cvt_pk_bf16_f32 v235, v48, v49
	v_cvt_pk_bf16_f32 v236, v42, v43
	v_cvt_pk_bf16_f32 v237, v44, v45
	global_store_dwordx4 v[148:149], v[234:237], off
	global_load_dwordx4 v[234:237], v[150:151], off offset:2304
	s_waitcnt vmcnt(8)
	v_lshlrev_b32_e32 v250, 16, v238
	v_and_b32_e32 v251, 0xffff0000, v238
	v_mul_f32_e32 v38, v38, v250
	v_mul_f32_e32 v39, v39, v251
	v_lshlrev_b32_e32 v252, 16, v239
	v_and_b32_e32 v253, 0xffff0000, v239
	v_mul_f32_e32 v40, v40, v252
	v_mul_f32_e32 v41, v41, v253
	v_lshlrev_b32_e32 v250, 16, v240
	v_and_b32_e32 v251, 0xffff0000, v240
	v_mul_f32_e32 v34, v34, v250
	v_mul_f32_e32 v35, v35, v251
	v_lshlrev_b32_e32 v252, 16, v241
	v_and_b32_e32 v253, 0xffff0000, v241
	v_mul_f32_e32 v36, v36, v252
	v_mul_f32_e32 v37, v37, v253
	v_cvt_pk_bf16_f32 v238, v38, v39
	v_cvt_pk_bf16_f32 v239, v40, v41
	v_cvt_pk_bf16_f32 v240, v34, v35
	v_cvt_pk_bf16_f32 v241, v36, v37
	global_store_dwordx4 v[148:149], v[238:241], off offset:256
	v_add_co_u32_e32 v148, vcc, 0x8000, v148
	s_nop 1
	v_addc_co_u32_e32 v149, vcc, 0, v149, vcc
	s_waitcnt vmcnt(7)
	v_lshlrev_b32_e32 v250, 16, v242
	v_and_b32_e32 v251, 0xffff0000, v242
	v_mul_f32_e32 v30, v30, v250
	v_mul_f32_e32 v31, v31, v251
	v_lshlrev_b32_e32 v252, 16, v243
	v_and_b32_e32 v253, 0xffff0000, v243
	v_mul_f32_e32 v32, v32, v252
	v_mul_f32_e32 v33, v33, v253
	v_lshlrev_b32_e32 v250, 16, v244
	v_and_b32_e32 v251, 0xffff0000, v244
	v_mul_f32_e32 v26, v26, v250
	v_mul_f32_e32 v27, v27, v251
	v_lshlrev_b32_e32 v252, 16, v245
	v_and_b32_e32 v253, 0xffff0000, v245
	v_mul_f32_e32 v28, v28, v252
	v_mul_f32_e32 v29, v29, v253
	v_cvt_pk_bf16_f32 v242, v30, v31
	v_cvt_pk_bf16_f32 v243, v32, v33
	v_cvt_pk_bf16_f32 v244, v26, v27
	v_cvt_pk_bf16_f32 v245, v28, v29
	global_store_dwordx4 v[148:149], v[242:245], off
	s_waitcnt vmcnt(6)
	v_lshlrev_b32_e32 v250, 16, v246
	v_and_b32_e32 v251, 0xffff0000, v246
	v_mul_f32_e32 v22, v22, v250
	v_mul_f32_e32 v23, v23, v251
	v_lshlrev_b32_e32 v252, 16, v247
	v_and_b32_e32 v253, 0xffff0000, v247
	v_mul_f32_e32 v24, v24, v252
	v_mul_f32_e32 v25, v25, v253
	v_lshlrev_b32_e32 v250, 16, v248
	v_and_b32_e32 v251, 0xffff0000, v248
	v_mul_f32_e32 v18, v18, v250
	v_mul_f32_e32 v19, v19, v251
	v_lshlrev_b32_e32 v252, 16, v249
	v_and_b32_e32 v253, 0xffff0000, v249
	v_mul_f32_e32 v20, v20, v252
	v_mul_f32_e32 v21, v21, v253
	v_cvt_pk_bf16_f32 v246, v22, v23
	v_cvt_pk_bf16_f32 v247, v24, v25
	v_cvt_pk_bf16_f32 v248, v18, v19
	v_cvt_pk_bf16_f32 v249, v20, v21
	global_store_dwordx4 v[148:149], v[246:249], off offset:256
	v_add_co_u32_e32 v148, vcc, 0x8000, v148
	s_nop 1
	v_addc_co_u32_e32 v149, vcc, 0, v149, vcc
	s_waitcnt vmcnt(5)
	v_lshlrev_b32_e32 v250, 16, v134
	v_and_b32_e32 v251, 0xffff0000, v134
	v_mul_f32_e32 v14, v14, v250
	v_mul_f32_e32 v15, v15, v251
	v_lshlrev_b32_e32 v252, 16, v135
	v_and_b32_e32 v253, 0xffff0000, v135
	v_mul_f32_e32 v16, v16, v252
	v_mul_f32_e32 v17, v17, v253
	v_lshlrev_b32_e32 v250, 16, v136
	v_and_b32_e32 v251, 0xffff0000, v136
	v_mul_f32_e32 v10, v10, v250
	v_mul_f32_e32 v11, v11, v251
	v_lshlrev_b32_e32 v252, 16, v137
	v_and_b32_e32 v253, 0xffff0000, v137
	v_mul_f32_e32 v12, v12, v252
	v_mul_f32_e32 v13, v13, v253
	v_cvt_pk_bf16_f32 v134, v14, v15
	v_cvt_pk_bf16_f32 v135, v16, v17
	v_cvt_pk_bf16_f32 v136, v10, v11
	v_cvt_pk_bf16_f32 v137, v12, v13
	global_store_dwordx4 v[148:149], v[134:137], off
	s_waitcnt vmcnt(4)
	v_lshlrev_b32_e32 v250, 16, v234
	v_and_b32_e32 v251, 0xffff0000, v234
	v_mul_f32_e32 v6, v6, v250
	v_mul_f32_e32 v7, v7, v251
	v_lshlrev_b32_e32 v252, 16, v235
	v_and_b32_e32 v253, 0xffff0000, v235
	v_mul_f32_e32 v8, v8, v252
	v_mul_f32_e32 v9, v9, v253
	v_lshlrev_b32_e32 v250, 16, v236
	v_and_b32_e32 v251, 0xffff0000, v236
	v_mul_f32_e32 v2, v2, v250
	v_mul_f32_e32 v3, v3, v251
	v_lshlrev_b32_e32 v252, 16, v237
	v_and_b32_e32 v253, 0xffff0000, v237
	v_mul_f32_e32 v4, v4, v252
	v_mul_f32_e32 v5, v5, v253
	v_cvt_pk_bf16_f32 v234, v6, v7
	v_cvt_pk_bf16_f32 v235, v8, v9
	v_cvt_pk_bf16_f32 v236, v2, v3
	v_cvt_pk_bf16_f32 v237, v4, v5
	global_store_dwordx4 v[148:149], v[234:237], off offset:256
	s_mov_b64 s[2:3], -1
	s_andn2_b64 vcc, exec, s[40:41]
	s_cbranch_vccnz .LBB0_204
	s_andn2_b64 vcc, exec, s[10:11]
	s_cbranch_vccnz .LBB0_203
	s_barrier
	s_branch .LBB0_203
